# grid barrier: acquire-side cache invalidate issued at barrier entry by wave 1 (overlapping the barrier protocol) instead of after release by every thread 0
# speedup vs baseline: 1.0112x; 1.0112x over previous
; __device__ __forceinline__ unsigned xb_ld(unsigned* p)              { return __hip_atomic_load(p, __ATOMIC_RELAXED, __HIP_MEMORY_SCOPE_AGENT); }
; __device__ __forceinline__ void xcd_barrier_complete(unsigned* bar, unsigned x, unsigned& nloc, unsigned& nx) {
;     const unsigned G = gridDim.x * gridDim.y * gridDim.z;
;     unsigned sum, cnt, mine, sp = 0u;
;     for (;;) {
;         sum = 0u; cnt = 0u; mine = 0u;
; #pragma unroll
;         for (unsigned j = 0; j < 16; ++j) { const unsigned c = xb_ld(&bar[XB_XCNT(j)]); sum += c; cnt += (c > 0u) ? 1u : 0u; mine = (j == x) ? c : mine; }
;         if (sum == G) break;
;         __builtin_amdgcn_s_sleep(1);
;         if ((++sp & 255u) == 0u) { if (xb_ld(&bar[XB_TMO])) break; if (sp > XB_SPIN_CAP) { atomicAdd(&bar[XB_TMO], 1u); break; } }
;     }
;     nloc = mine > 0u ? mine : 1u; nx = cnt > 0u ? cnt : 1u;
; }
; __device__ __forceinline__ void xcd_barrier(const XcdBarrier& b) {
;     asm volatile("s_waitcnt vmcnt(0)" ::: "memory");
;     __syncthreads();
;     if (threadIdx.x == 0) {
;         unsigned* bar = b.bar;
;         __builtin_amdgcn_s_waitcnt(0);
;         unsigned nloc = b.st[0], nx = b.st[1];
;         if (nloc == 0u) { xcd_barrier_complete(bar, b.x, nloc, nx); b.st[0] = nloc; b.st[1] = nx; }
.Linit_done:
	s_or_b64 exec, exec, s[4:5]
	s_waitcnt vmcnt(0)
	s_waitcnt lgkmcnt(0)
	s_barrier
	v_readfirstlane_b32 s2, v152
	s_cmp_lg_u32 s2, 64
	s_cbranch_scc1 .Leinv_skip_0
	buffer_inv sc1
	s_waitcnt vmcnt(0)
.Leinv_skip_0:
	s_mov_b64 s[0:1], exec
	v_readlane_b32 s2, v255, 2
	v_readlane_b32 s3, v255, 3
	s_and_b64 s[2:3], s[0:1], s[2:3]
	s_mov_b64 exec, s[2:3]
	s_cbranch_execz .LBB0_115
	s_add_i32 s2, 0, 0x20000
	v_mov_b32_e32 v0, s2
	s_waitcnt vmcnt(0) expcnt(0) lgkmcnt(0)
	ds_read_b32 v2, v0
	s_add_i32 s2, 0, 0x20004
	v_mov_b32_e32 v0, s2
	ds_read_b32 v0, v0
	s_waitcnt lgkmcnt(1)
	v_cmp_ne_u32_e32 vcc, 0, v2
	s_cbranch_vccnz .LBB0_79
	s_add_u32 s4, s72, 0x580200
	s_addc_u32 s5, s73, 0
	s_add_u32 s6, s72, 0x580400
	s_addc_u32 s7, s73, 0
	s_add_u32 s8, s72, 0x580500
	s_addc_u32 s9, s73, 0
	s_add_u32 s10, s72, 0x580600
	s_addc_u32 s11, s73, 0
	s_add_u32 s12, s72, 0x580700
	s_addc_u32 s13, s73, 0
	s_add_u32 s14, s72, 0x580800
	s_addc_u32 s15, s73, 0
	s_add_u32 s28, s72, 0x580900
	s_addc_u32 s29, s73, 0
	s_add_u32 s30, s72, 0x580a00
	s_addc_u32 s31, s73, 0
	s_add_u32 s34, s72, 0x580b00
	s_addc_u32 s35, s73, 0
	s_add_u32 s36, s72, 0x580c00
	s_addc_u32 s37, s73, 0
	s_add_u32 s38, s72, 0x580d00
	s_addc_u32 s39, s73, 0
	s_add_u32 s40, s72, 0x580e00
	s_addc_u32 s41, s73, 0
	s_add_u32 s42, s72, 0x580f00
	s_addc_u32 s43, s73, 0
	s_add_u32 s44, s72, 0x581000
	s_addc_u32 s45, s73, 0
	s_add_u32 s46, s72, 0x581100
	s_addc_u32 s47, s73, 0
	s_add_u32 s76, s72, 0x581200
	v_readlane_b32 s2, v255, 0
	s_addc_u32 s77, s73, 0
	s_mul_i32 s2, s75, s2
	s_add_u32 s78, s72, 0x581300
	s_mul_i32 s2, s2, s74
	s_addc_u32 s79, s73, 0
	s_mov_b32 s3, 1
	v_mov_b32_e32 v16, 0
	s_branch .LBB0_66

; __device__ __forceinline__ unsigned xb_ld(unsigned* p)              { return __hip_atomic_load(p, __ATOMIC_RELAXED, __HIP_MEMORY_SCOPE_AGENT); }
; #define XB_SPIN(cond, bar) do { unsigned _sp = 0; while (cond) { __builtin_amdgcn_s_sleep(1); \
;     if ((++_sp & 255u) == 0u) { if (xb_ld(&(bar)[XB_TMO])) break; if (_sp > XB_SPIN_CAP) { atomicAdd(&(bar)[XB_TMO], 1u); break; } } } } while (0)
; __device__ __forceinline__ void xcd_barrier(const XcdBarrier& b) {
;     ...
;             XB_SPIN(xb_ld(&bar[XB_XGEN(b.x)]) == gen, bar);
;             __builtin_amdgcn_fence(__ATOMIC_ACQUIRE, "agent");
;             asm volatile("s_waitcnt vmcnt(0)" ::: "memory");
.LBB0_94:
	s_or_b64 exec, exec, s[8:9]
	s_waitcnt vmcnt(0)
	s_waitcnt vmcnt(0)

; __device__ __forceinline__ unsigned xb_ld(unsigned* p)              { return __hip_atomic_load(p, __ATOMIC_RELAXED, __HIP_MEMORY_SCOPE_AGENT); }
; __device__ __forceinline__ unsigned xb_add(unsigned* p, unsigned v) { return __hip_atomic_fetch_add(p, v, __ATOMIC_RELAXED, __HIP_MEMORY_SCOPE_AGENT); }
; #define XB_SPIN(cond, bar) do { unsigned _sp = 0; while (cond) { __builtin_amdgcn_s_sleep(1); \
;     if ((++_sp & 255u) == 0u) { if (xb_ld(&(bar)[XB_TMO])) break; if (_sp > XB_SPIN_CAP) { atomicAdd(&(bar)[XB_TMO], 1u); break; } } } } while (0)
; __device__ __forceinline__ void xcd_barrier(const XcdBarrier& b) {
;     ...
;             else XB_SPIN(xb_ld(&bar[XB_TOPGEN]) == tg, bar);
;             __builtin_amdgcn_fence(__ATOMIC_ACQUIRE, "agent");
;             xb_add(&bar[XB_XGEN(b.x)], 1u);
;             asm volatile("s_waitcnt vmcnt(0)" ::: "memory");
.LBB0_112:
	s_or_b64 exec, exec, s[6:7]
	s_mov_b64 s[6:7], exec
	v_mbcnt_lo_u32_b32 v0, s6, 0
	v_mbcnt_hi_u32_b32 v0, s7, v0
	v_cmp_eq_u32_e32 vcc, 0, v0
	s_waitcnt vmcnt(0)
	s_and_saveexec_b64 s[8:9], vcc
	s_cbranch_execz .LBB0_114
	s_bcnt1_i32_b64 s2, s[6:7]
	v_mov_b32_e32 v0, 0x2000
	v_mov_b32_e32 v1, s2
	global_atomic_add v0, v1, s[4:5] offset:1024

; __device__ __forceinline__ unsigned xb_ld(unsigned* p)              { return __hip_atomic_load(p, __ATOMIC_RELAXED, __HIP_MEMORY_SCOPE_AGENT); }
; __device__ __forceinline__ void xcd_barrier_complete(unsigned* bar, unsigned x, unsigned& nloc, unsigned& nx) {
;     const unsigned G = gridDim.x * gridDim.y * gridDim.z;
;     unsigned sum, cnt, mine, sp = 0u;
;     for (;;) {
;         sum = 0u; cnt = 0u; mine = 0u;
; #pragma unroll
;         for (unsigned j = 0; j < 16; ++j) { const unsigned c = xb_ld(&bar[XB_XCNT(j)]); sum += c; cnt += (c > 0u) ? 1u : 0u; mine = (j == x) ? c : mine; }
;         if (sum == G) break;
;         __builtin_amdgcn_s_sleep(1);
;         if ((++sp & 255u) == 0u) { if (xb_ld(&bar[XB_TMO])) break; if (sp > XB_SPIN_CAP) { atomicAdd(&bar[XB_TMO], 1u); break; } }
;     }
;     nloc = mine > 0u ? mine : 1u; nx = cnt > 0u ? cnt : 1u;
; }
; __device__ __forceinline__ void xcd_barrier(const XcdBarrier& b) {
;     asm volatile("s_waitcnt vmcnt(0)" ::: "memory");
;     __syncthreads();
;     if (threadIdx.x == 0) {
;         unsigned* bar = b.bar;
;         __builtin_amdgcn_s_waitcnt(0);
;         unsigned nloc = b.st[0], nx = b.st[1];
;         if (nloc == 0u) { xcd_barrier_complete(bar, b.x, nloc, nx); b.st[0] = nloc; b.st[1] = nx; }
.LBB0_296:
	s_waitcnt vmcnt(0)
	s_waitcnt vmcnt(0)
	s_barrier
	v_readfirstlane_b32 s2, v152
	s_cmp_lg_u32 s2, 64
	s_cbranch_scc1 .Leinv_skip_1
	buffer_inv sc1
	s_waitcnt vmcnt(0)
.Leinv_skip_1:
	s_mov_b64 s[0:1], exec
	v_readlane_b32 s2, v255, 2
	v_readlane_b32 s3, v255, 3
	s_and_b64 s[2:3], s[0:1], s[2:3]
	s_mov_b64 exec, s[2:3]
	s_cbranch_execz .LBB0_349
	s_add_i32 s2, 0, 0x20000
	v_mov_b32_e32 v0, s2
	s_waitcnt vmcnt(0) expcnt(0) lgkmcnt(0)
	ds_read_b32 v2, v0
	s_add_i32 s2, 0, 0x20004
	v_mov_b32_e32 v0, s2
	ds_read_b32 v0, v0
	s_waitcnt lgkmcnt(1)
	v_cmp_ne_u32_e32 vcc, 0, v2
	s_cbranch_vccnz .LBB0_312
	s_add_u32 s4, s72, 0x580200
	s_addc_u32 s5, s73, 0
	s_add_u32 s6, s72, 0x580400
	s_addc_u32 s7, s73, 0
	s_add_u32 s8, s72, 0x580500
	s_addc_u32 s9, s73, 0
	s_add_u32 s10, s72, 0x580600
	s_addc_u32 s11, s73, 0
	s_add_u32 s12, s72, 0x580700
	s_addc_u32 s13, s73, 0
	s_add_u32 s14, s72, 0x580800
	s_addc_u32 s15, s73, 0
	s_add_u32 s16, s72, 0x580900
	s_addc_u32 s17, s73, 0
	s_add_u32 s18, s72, 0x580a00
	s_addc_u32 s19, s73, 0
	s_add_u32 s20, s72, 0x580b00
	s_addc_u32 s21, s73, 0
	s_add_u32 s24, s72, 0x580c00
	s_addc_u32 s25, s73, 0
	s_add_u32 s26, s72, 0x580d00
	s_addc_u32 s27, s73, 0
	s_add_u32 s28, s72, 0x580e00
	s_addc_u32 s29, s73, 0
	s_add_u32 s30, s72, 0x580f00
	s_addc_u32 s31, s73, 0
	s_add_u32 s34, s72, 0x581000
	s_addc_u32 s35, s73, 0
	s_add_u32 s36, s72, 0x581100
	s_addc_u32 s37, s73, 0
	s_add_u32 s38, s72, 0x581200
	v_readlane_b32 s2, v255, 0
	s_addc_u32 s39, s73, 0
	s_mul_i32 s2, s75, s2
	s_add_u32 s40, s72, 0x581300
	s_mul_i32 s2, s2, s74
	s_addc_u32 s41, s73, 0
	s_mov_b32 s3, 1
	v_mov_b32_e32 v16, 0
	s_branch .LBB0_300

; __device__ __forceinline__ unsigned xb_ld(unsigned* p)              { return __hip_atomic_load(p, __ATOMIC_RELAXED, __HIP_MEMORY_SCOPE_AGENT); }
; __device__ __forceinline__ void xcd_barrier_complete(unsigned* bar, unsigned x, unsigned& nloc, unsigned& nx) {
;     const unsigned G = gridDim.x * gridDim.y * gridDim.z;
;     unsigned sum, cnt, mine, sp = 0u;
;     for (;;) {
;         sum = 0u; cnt = 0u; mine = 0u;
; #pragma unroll
;         for (unsigned j = 0; j < 16; ++j) { const unsigned c = xb_ld(&bar[XB_XCNT(j)]); sum += c; cnt += (c > 0u) ? 1u : 0u; mine = (j == x) ? c : mine; }
;         if (sum == G) break;
;         __builtin_amdgcn_s_sleep(1);
;         if ((++sp & 255u) == 0u) { if (xb_ld(&bar[XB_TMO])) break; if (sp > XB_SPIN_CAP) { atomicAdd(&bar[XB_TMO], 1u); break; } }
;     }
;     nloc = mine > 0u ? mine : 1u; nx = cnt > 0u ? cnt : 1u;
; }
; __device__ __forceinline__ void xcd_barrier(const XcdBarrier& b) {
;     asm volatile("s_waitcnt vmcnt(0)" ::: "memory");
;     __syncthreads();
;     if (threadIdx.x == 0) {
;         unsigned* bar = b.bar;
;         __builtin_amdgcn_s_waitcnt(0);
;         unsigned nloc = b.st[0], nx = b.st[1];
;         if (nloc == 0u) { xcd_barrier_complete(bar, b.x, nloc, nx); b.st[0] = nloc; b.st[1] = nx; }
.LBB0_395:
	s_waitcnt vmcnt(0)
	s_waitcnt lgkmcnt(0)
	s_barrier
	v_readfirstlane_b32 s2, v152
	s_cmp_lg_u32 s2, 64
	s_cbranch_scc1 .Leinv_skip_2
	buffer_inv sc1
	s_waitcnt vmcnt(0)
.Leinv_skip_2:
	s_mov_b64 s[0:1], exec
	v_readlane_b32 s2, v255, 2
	v_readlane_b32 s3, v255, 3
	s_and_b64 s[2:3], s[0:1], s[2:3]
	s_mov_b64 exec, s[2:3]
	s_cbranch_execz .LBB0_447
	s_add_i32 s2, 0, 0x20000
	v_mov_b32_e32 v0, s2
	s_waitcnt vmcnt(0) expcnt(0) lgkmcnt(0)
	ds_read_b32 v2, v0
	s_add_i32 s2, 0, 0x20004
	v_mov_b32_e32 v0, s2
	ds_read_b32 v0, v0
	s_waitcnt lgkmcnt(1)
	v_cmp_ne_u32_e32 vcc, 0, v2
	s_cbranch_vccnz .LBB0_411
	s_add_u32 s4, s72, 0x580200
	s_addc_u32 s5, s73, 0
	s_add_u32 s6, s72, 0x580400
	s_addc_u32 s7, s73, 0
	s_add_u32 s8, s72, 0x580500
	s_addc_u32 s9, s73, 0
	s_add_u32 s10, s72, 0x580600
	s_addc_u32 s11, s73, 0
	s_add_u32 s12, s72, 0x580700
	s_addc_u32 s13, s73, 0
	s_add_u32 s16, s72, 0x580800
	s_addc_u32 s17, s73, 0
	s_add_u32 s18, s72, 0x580900
	s_addc_u32 s19, s73, 0
	s_add_u32 s20, s72, 0x580a00
	s_addc_u32 s21, s73, 0
	s_add_u32 s24, s72, 0x580b00
	s_addc_u32 s25, s73, 0
	s_add_u32 s26, s72, 0x580c00
	s_addc_u32 s27, s73, 0
	s_add_u32 s28, s72, 0x580d00
	s_addc_u32 s29, s73, 0
	s_add_u32 s30, s72, 0x580e00
	s_addc_u32 s31, s73, 0
	s_add_u32 s34, s72, 0x580f00
	s_addc_u32 s35, s73, 0
	s_add_u32 s36, s72, 0x581000
	s_addc_u32 s37, s73, 0
	s_add_u32 s38, s72, 0x581100
	s_addc_u32 s39, s73, 0
	s_add_u32 s40, s72, 0x581200
	v_readlane_b32 s2, v255, 0
	s_addc_u32 s41, s73, 0
	s_mul_i32 s2, s75, s2
	s_add_u32 s42, s72, 0x581300
	s_mul_i32 s2, s2, s74
	s_addc_u32 s43, s73, 0
	s_mov_b32 s3, 1
	v_mov_b32_e32 v16, 0
	s_branch .LBB0_399

; __device__ __forceinline__ unsigned xb_ld(unsigned* p)              { return __hip_atomic_load(p, __ATOMIC_RELAXED, __HIP_MEMORY_SCOPE_AGENT); }
; __device__ __forceinline__ void xcd_barrier_complete(unsigned* bar, unsigned x, unsigned& nloc, unsigned& nx) {
;     const unsigned G = gridDim.x * gridDim.y * gridDim.z;
;     unsigned sum, cnt, mine, sp = 0u;
;     for (;;) {
;         sum = 0u; cnt = 0u; mine = 0u;
; #pragma unroll
;         for (unsigned j = 0; j < 16; ++j) { const unsigned c = xb_ld(&bar[XB_XCNT(j)]); sum += c; cnt += (c > 0u) ? 1u : 0u; mine = (j == x) ? c : mine; }
;         if (sum == G) break;
;         __builtin_amdgcn_s_sleep(1);
;         if ((++sp & 255u) == 0u) { if (xb_ld(&bar[XB_TMO])) break; if (sp > XB_SPIN_CAP) { atomicAdd(&bar[XB_TMO], 1u); break; } }
;     }
;     nloc = mine > 0u ? mine : 1u; nx = cnt > 0u ? cnt : 1u;
; }
; __device__ __forceinline__ void xcd_barrier(const XcdBarrier& b) {
;     asm volatile("s_waitcnt vmcnt(0)" ::: "memory");
;     __syncthreads();
;     if (threadIdx.x == 0) {
;         unsigned* bar = b.bar;
;         __builtin_amdgcn_s_waitcnt(0);
;         unsigned nloc = b.st[0], nx = b.st[1];
;         if (nloc == 0u) { xcd_barrier_complete(bar, b.x, nloc, nx); b.st[0] = nloc; b.st[1] = nx; }
.Leinv_skip_3:
	s_mov_b64 s[0:1], exec
	v_readlane_b32 s2, v255, 2
	v_readlane_b32 s3, v255, 3
	s_and_b64 s[2:3], s[0:1], s[2:3]
	s_mov_b64 exec, s[2:3]
	s_cbranch_execz .LBB0_608
	s_add_i32 s2, 0, 0x20000
	v_mov_b32_e32 v0, s2
	s_waitcnt vmcnt(0) expcnt(0) lgkmcnt(0)
	ds_read_b32 v2, v0
	s_add_i32 s2, 0, 0x20004
	v_mov_b32_e32 v0, s2
	ds_read_b32 v0, v0
	s_waitcnt lgkmcnt(1)
	v_cmp_ne_u32_e32 vcc, 0, v2
	s_cbranch_vccnz .LBB0_571
	s_add_u32 s4, s72, 0x580200
	s_addc_u32 s5, s73, 0
	s_add_u32 s6, s72, 0x580400
	s_addc_u32 s7, s73, 0
	s_add_u32 s8, s72, 0x580500
	s_addc_u32 s9, s73, 0
	s_add_u32 s10, s72, 0x580600
	s_addc_u32 s11, s73, 0
	s_add_u32 s12, s72, 0x580700
	s_addc_u32 s13, s73, 0
	s_add_u32 s14, s72, 0x580800
	s_addc_u32 s15, s73, 0
	s_add_u32 s16, s72, 0x580900
	s_addc_u32 s17, s73, 0
	s_add_u32 s18, s72, 0x580a00
	s_addc_u32 s19, s73, 0
	s_add_u32 s20, s72, 0x580b00
	s_addc_u32 s21, s73, 0
	s_add_u32 s22, s72, 0x580c00
	s_addc_u32 s23, s73, 0
	s_add_u32 s24, s72, 0x580d00
	s_addc_u32 s25, s73, 0
	s_add_u32 s26, s72, 0x580e00
	s_addc_u32 s27, s73, 0
	s_add_u32 s28, s72, 0x580f00
	s_addc_u32 s29, s73, 0
	s_add_u32 s30, s72, 0x581000
	s_addc_u32 s31, s73, 0
	s_add_u32 s34, s72, 0x581100
	s_addc_u32 s35, s73, 0
	s_add_u32 s36, s72, 0x581200
	v_readlane_b32 s2, v255, 0
	s_addc_u32 s37, s73, 0
	s_mul_i32 s2, s75, s2
	s_add_u32 s38, s72, 0x581300
	s_mul_i32 s2, s2, s74
	s_addc_u32 s39, s73, 0
	s_mov_b32 s3, 1
	v_mov_b32_e32 v16, 0
	s_branch .LBB0_559

; __device__ __forceinline__ unsigned xb_ld(unsigned* p)              { return __hip_atomic_load(p, __ATOMIC_RELAXED, __HIP_MEMORY_SCOPE_AGENT); }
; __device__ __forceinline__ void xcd_barrier_complete(unsigned* bar, unsigned x, unsigned& nloc, unsigned& nx) {
;     const unsigned G = gridDim.x * gridDim.y * gridDim.z;
;     unsigned sum, cnt, mine, sp = 0u;
;     for (;;) {
;         sum = 0u; cnt = 0u; mine = 0u;
; #pragma unroll
;         for (unsigned j = 0; j < 16; ++j) { const unsigned c = xb_ld(&bar[XB_XCNT(j)]); sum += c; cnt += (c > 0u) ? 1u : 0u; mine = (j == x) ? c : mine; }
;         if (sum == G) break;
;         __builtin_amdgcn_s_sleep(1);
;         if ((++sp & 255u) == 0u) { if (xb_ld(&bar[XB_TMO])) break; if (sp > XB_SPIN_CAP) { atomicAdd(&bar[XB_TMO], 1u); break; } }
;     }
;     nloc = mine > 0u ? mine : 1u; nx = cnt > 0u ? cnt : 1u;
; }
; __device__ __forceinline__ void xcd_barrier(const XcdBarrier& b) {
;     asm volatile("s_waitcnt vmcnt(0)" ::: "memory");
;     __syncthreads();
;     if (threadIdx.x == 0) {
;         unsigned* bar = b.bar;
;         __builtin_amdgcn_s_waitcnt(0);
;         unsigned nloc = b.st[0], nx = b.st[1];
;         if (nloc == 0u) { xcd_barrier_complete(bar, b.x, nloc, nx); b.st[0] = nloc; b.st[1] = nx; }
.LBB0_977:
	s_waitcnt vmcnt(0)
	s_barrier
	v_readfirstlane_b32 s2, v152
	s_cmp_lg_u32 s2, 64
	s_cbranch_scc1 .Leinv_skip_4
	buffer_inv sc1
	s_waitcnt vmcnt(0)
.Leinv_skip_4:
	s_mov_b64 s[0:1], exec
	v_readlane_b32 s2, v255, 2
	v_readlane_b32 s3, v255, 3
	s_and_b64 s[2:3], s[0:1], s[2:3]
	s_mov_b64 exec, s[2:3]
	s_cbranch_execz .LBB0_1029
	s_add_i32 s2, 0, 0x20000
	v_mov_b32_e32 v0, s2
	s_waitcnt vmcnt(0) expcnt(0) lgkmcnt(0)
	ds_read_b32 v2, v0
	s_add_i32 s2, 0, 0x20004
	v_mov_b32_e32 v0, s2
	ds_read_b32 v0, v0
	s_waitcnt lgkmcnt(1)
	v_cmp_ne_u32_e32 vcc, 0, v2
	s_cbranch_vccnz .LBB0_993
	s_add_u32 s4, s72, 0x580200
	s_addc_u32 s5, s73, 0
	s_add_u32 s6, s72, 0x580400
	s_addc_u32 s7, s73, 0
	s_add_u32 s8, s72, 0x580500
	s_addc_u32 s9, s73, 0
	s_add_u32 s10, s72, 0x580600
	s_addc_u32 s11, s73, 0
	s_add_u32 s12, s72, 0x580700
	s_addc_u32 s13, s73, 0
	s_add_u32 s14, s72, 0x580800
	s_addc_u32 s15, s73, 0
	s_add_u32 s16, s72, 0x580900
	s_addc_u32 s17, s73, 0
	s_add_u32 s18, s72, 0x580a00
	s_addc_u32 s19, s73, 0
	s_add_u32 s20, s72, 0x580b00
	s_addc_u32 s21, s73, 0
	s_add_u32 s22, s72, 0x580c00
	s_addc_u32 s23, s73, 0
	s_add_u32 s24, s72, 0x580d00
	s_addc_u32 s25, s73, 0
	s_add_u32 s26, s72, 0x580e00
	s_addc_u32 s27, s73, 0
	s_add_u32 s28, s72, 0x580f00
	s_addc_u32 s29, s73, 0
	s_add_u32 s30, s72, 0x581000
	s_addc_u32 s31, s73, 0
	s_add_u32 s38, s72, 0x581100
	s_addc_u32 s39, s73, 0
	s_add_u32 s40, s72, 0x581200
	v_readlane_b32 s2, v255, 0
	s_addc_u32 s41, s73, 0
	s_mul_i32 s2, s75, s2
	s_add_u32 s42, s72, 0x581300
	s_mul_i32 s2, s2, s74
	s_addc_u32 s43, s73, 0
	s_mov_b32 s3, 1
	v_mov_b32_e32 v16, 0
	s_branch .LBB0_981

; __device__ __forceinline__ unsigned xb_ld(unsigned* p)              { return __hip_atomic_load(p, __ATOMIC_RELAXED, __HIP_MEMORY_SCOPE_AGENT); }
; __device__ __forceinline__ void xcd_barrier_complete(unsigned* bar, unsigned x, unsigned& nloc, unsigned& nx) {
;     const unsigned G = gridDim.x * gridDim.y * gridDim.z;
;     unsigned sum, cnt, mine, sp = 0u;
;     for (;;) {
;         sum = 0u; cnt = 0u; mine = 0u;
; #pragma unroll
;         for (unsigned j = 0; j < 16; ++j) { const unsigned c = xb_ld(&bar[XB_XCNT(j)]); sum += c; cnt += (c > 0u) ? 1u : 0u; mine = (j == x) ? c : mine; }
;         if (sum == G) break;
;         __builtin_amdgcn_s_sleep(1);
;         if ((++sp & 255u) == 0u) { if (xb_ld(&bar[XB_TMO])) break; if (sp > XB_SPIN_CAP) { atomicAdd(&bar[XB_TMO], 1u); break; } }
;     }
;     nloc = mine > 0u ? mine : 1u; nx = cnt > 0u ? cnt : 1u;
; }
; __device__ __forceinline__ void xcd_barrier(const XcdBarrier& b) {
;     asm volatile("s_waitcnt vmcnt(0)" ::: "memory");
;     __syncthreads();
;     if (threadIdx.x == 0) {
;         unsigned* bar = b.bar;
;         __builtin_amdgcn_s_waitcnt(0);
;         unsigned nloc = b.st[0], nx = b.st[1];
;         if (nloc == 0u) { xcd_barrier_complete(bar, b.x, nloc, nx); b.st[0] = nloc; b.st[1] = nx; }
.Leinv_skip_5:
	s_mov_b64 s[4:5], exec
	v_readlane_b32 s2, v255, 2
	v_readlane_b32 s3, v255, 3
	s_and_b64 s[2:3], s[4:5], s[2:3]
	s_mov_b64 exec, s[2:3]
	s_cbranch_execz .LBB0_1114
	s_add_i32 s2, 0, 0x20000
	v_mov_b32_e32 v0, s2
	s_waitcnt vmcnt(0) expcnt(0) lgkmcnt(0)
	ds_read_b32 v2, v0
	s_add_i32 s2, 0, 0x20004
	v_mov_b32_e32 v0, s2
	ds_read_b32 v0, v0
	s_waitcnt lgkmcnt(1)
	v_cmp_ne_u32_e32 vcc, 0, v2
	s_cbranch_vccnz .LBB0_1078
	s_add_u32 s6, s72, 0x580200
	s_addc_u32 s7, s73, 0
	s_add_u32 s8, s72, 0x580400
	s_addc_u32 s9, s73, 0
	s_add_u32 s10, s72, 0x580500
	s_addc_u32 s11, s73, 0
	s_add_u32 s12, s72, 0x580600
	s_addc_u32 s13, s73, 0
	s_add_u32 s14, s72, 0x580700
	s_addc_u32 s15, s73, 0
	s_add_u32 s16, s72, 0x580800
	s_addc_u32 s17, s73, 0
	s_add_u32 s18, s72, 0x580900
	s_addc_u32 s19, s73, 0
	s_add_u32 s20, s72, 0x580a00
	s_addc_u32 s21, s73, 0
	s_add_u32 s22, s72, 0x580b00
	s_addc_u32 s23, s73, 0
	s_add_u32 s24, s72, 0x580c00
	s_addc_u32 s25, s73, 0
	s_add_u32 s26, s72, 0x580d00
	s_addc_u32 s27, s73, 0
	s_add_u32 s28, s72, 0x580e00
	s_addc_u32 s29, s73, 0
	s_add_u32 s30, s72, 0x580f00
	s_addc_u32 s31, s73, 0
	s_add_u32 s34, s72, 0x581000
	s_addc_u32 s35, s73, 0
	s_add_u32 s36, s72, 0x581100
	s_addc_u32 s37, s73, 0
	s_add_u32 s38, s72, 0x581200
	v_readlane_b32 s2, v255, 0
	s_addc_u32 s39, s73, 0
	s_mul_i32 s2, s75, s2
	s_add_u32 s40, s72, 0x581300
	s_mul_i32 s2, s2, s74
	s_addc_u32 s41, s73, 0
	s_mov_b32 s3, 1
	v_mov_b32_e32 v16, 0
	s_branch .LBB0_1066

; __device__ __forceinline__ unsigned xb_ld(unsigned* p)              { return __hip_atomic_load(p, __ATOMIC_RELAXED, __HIP_MEMORY_SCOPE_AGENT); }
; #define XB_SPIN(cond, bar) do { unsigned _sp = 0; while (cond) { __builtin_amdgcn_s_sleep(1); \
;     if ((++_sp & 255u) == 0u) { if (xb_ld(&(bar)[XB_TMO])) break; if (_sp > XB_SPIN_CAP) { atomicAdd(&(bar)[XB_TMO], 1u); break; } } } } while (0)
; __device__ __forceinline__ void xcd_barrier(const XcdBarrier& b) {
;     ...
;             XB_SPIN(xb_ld(&bar[XB_XGEN(b.x)]) == gen, bar);
;             __builtin_amdgcn_fence(__ATOMIC_ACQUIRE, "agent");
;             asm volatile("s_waitcnt vmcnt(0)" ::: "memory");
.LBB0_1093:
	s_or_b64 exec, exec, s[10:11]
	s_waitcnt vmcnt(0)
	s_waitcnt vmcnt(0)

; __device__ __forceinline__ unsigned xb_ld(unsigned* p)              { return __hip_atomic_load(p, __ATOMIC_RELAXED, __HIP_MEMORY_SCOPE_AGENT); }
; __device__ __forceinline__ unsigned xb_add(unsigned* p, unsigned v) { return __hip_atomic_fetch_add(p, v, __ATOMIC_RELAXED, __HIP_MEMORY_SCOPE_AGENT); }
; #define XB_SPIN(cond, bar) do { unsigned _sp = 0; while (cond) { __builtin_amdgcn_s_sleep(1); \
;     if ((++_sp & 255u) == 0u) { if (xb_ld(&(bar)[XB_TMO])) break; if (_sp > XB_SPIN_CAP) { atomicAdd(&(bar)[XB_TMO], 1u); break; } } } } while (0)
; __device__ __forceinline__ void xcd_barrier(const XcdBarrier& b) {
;     ...
;             else XB_SPIN(xb_ld(&bar[XB_TOPGEN]) == tg, bar);
;             __builtin_amdgcn_fence(__ATOMIC_ACQUIRE, "agent");
;             xb_add(&bar[XB_XGEN(b.x)], 1u);
;             asm volatile("s_waitcnt vmcnt(0)" ::: "memory");
.LBB0_1111:
	s_or_b64 exec, exec, s[8:9]
	s_mov_b64 s[8:9], exec
	v_mbcnt_lo_u32_b32 v0, s8, 0
	v_mbcnt_hi_u32_b32 v0, s9, v0
	v_cmp_eq_u32_e32 vcc, 0, v0
	s_waitcnt vmcnt(0)
	s_and_saveexec_b64 s[10:11], vcc
	s_cbranch_execz .LBB0_1113
	s_bcnt1_i32_b64 s2, s[8:9]
	v_mov_b32_e32 v0, 0x2000
	v_mov_b32_e32 v1, s2
	global_atomic_add v0, v1, s[6:7] offset:1024

; __device__ __forceinline__ unsigned xb_ld(unsigned* p)              { return __hip_atomic_load(p, __ATOMIC_RELAXED, __HIP_MEMORY_SCOPE_AGENT); }
; __device__ __forceinline__ void xcd_barrier_complete(unsigned* bar, unsigned x, unsigned& nloc, unsigned& nx) {
;     const unsigned G = gridDim.x * gridDim.y * gridDim.z;
;     unsigned sum, cnt, mine, sp = 0u;
;     for (;;) {
;         sum = 0u; cnt = 0u; mine = 0u;
; #pragma unroll
;         for (unsigned j = 0; j < 16; ++j) { const unsigned c = xb_ld(&bar[XB_XCNT(j)]); sum += c; cnt += (c > 0u) ? 1u : 0u; mine = (j == x) ? c : mine; }
;         if (sum == G) break;
;         __builtin_amdgcn_s_sleep(1);
;         if ((++sp & 255u) == 0u) { if (xb_ld(&bar[XB_TMO])) break; if (sp > XB_SPIN_CAP) { atomicAdd(&bar[XB_TMO], 1u); break; } }
;     }
;     nloc = mine > 0u ? mine : 1u; nx = cnt > 0u ? cnt : 1u;
; }
; __device__ __forceinline__ void xcd_barrier(const XcdBarrier& b) {
;     asm volatile("s_waitcnt vmcnt(0)" ::: "memory");
;     __syncthreads();
;     if (threadIdx.x == 0) {
;         unsigned* bar = b.bar;
;         __builtin_amdgcn_s_waitcnt(0);
;         unsigned nloc = b.st[0], nx = b.st[1];
;         if (nloc == 0u) { xcd_barrier_complete(bar, b.x, nloc, nx); b.st[0] = nloc; b.st[1] = nx; }
.Leinv_skip_6:
	s_mov_b64 s[0:1], exec
	v_readlane_b32 s2, v255, 2
	v_readlane_b32 s3, v255, 3
	s_and_b64 s[2:3], s[0:1], s[2:3]
	s_mov_b64 exec, s[2:3]
	s_cbranch_execz .LBB0_1211
	s_add_i32 s2, 0, 0x20000
	s_waitcnt vmcnt(15)
	v_mov_b32_e32 v0, s2
	s_waitcnt vmcnt(0) expcnt(0) lgkmcnt(0)
	ds_read_b32 v2, v0
	s_add_i32 s2, 0, 0x20004
	v_mov_b32_e32 v0, s2
	ds_read_b32 v0, v0
	s_waitcnt lgkmcnt(1)
	v_cmp_ne_u32_e32 vcc, 0, v2
	s_cbranch_vccnz .LBB0_1175
	s_add_u32 s4, s72, 0x580200
	s_addc_u32 s5, s73, 0
	s_add_u32 s6, s72, 0x580400
	s_addc_u32 s7, s73, 0
	s_add_u32 s8, s72, 0x580500
	s_addc_u32 s9, s73, 0
	s_add_u32 s10, s72, 0x580600
	s_addc_u32 s11, s73, 0
	s_add_u32 s12, s72, 0x580700
	s_addc_u32 s13, s73, 0
	s_add_u32 s14, s72, 0x580800
	s_addc_u32 s15, s73, 0
	s_add_u32 s16, s72, 0x580900
	s_addc_u32 s17, s73, 0
	s_add_u32 s18, s72, 0x580a00
	s_addc_u32 s19, s73, 0
	s_add_u32 s20, s72, 0x580b00
	s_addc_u32 s21, s73, 0
	s_add_u32 s22, s72, 0x580c00
	s_addc_u32 s23, s73, 0
	s_add_u32 s24, s72, 0x580d00
	s_addc_u32 s25, s73, 0
	s_add_u32 s26, s72, 0x580e00
	s_addc_u32 s27, s73, 0
	s_add_u32 s28, s72, 0x580f00
	s_addc_u32 s29, s73, 0
	s_add_u32 s30, s72, 0x581000
	s_addc_u32 s31, s73, 0
	s_add_u32 s34, s72, 0x581100
	s_addc_u32 s35, s73, 0
	s_add_u32 s36, s72, 0x581200
	v_readlane_b32 s2, v255, 0
	s_addc_u32 s37, s73, 0
	s_mul_i32 s2, s75, s2
	s_add_u32 s38, s72, 0x581300
	s_mul_i32 s2, s2, s74
	s_addc_u32 s39, s73, 0
	s_mov_b32 s3, 1
	v_mov_b32_e32 v16, 0
	s_branch .LBB0_1163

; __device__ __forceinline__ unsigned xb_ld(unsigned* p)              { return __hip_atomic_load(p, __ATOMIC_RELAXED, __HIP_MEMORY_SCOPE_AGENT); }
; __device__ __forceinline__ void xcd_barrier_complete(unsigned* bar, unsigned x, unsigned& nloc, unsigned& nx) {
;     const unsigned G = gridDim.x * gridDim.y * gridDim.z;
;     unsigned sum, cnt, mine, sp = 0u;
;     for (;;) {
;         sum = 0u; cnt = 0u; mine = 0u;
; #pragma unroll
;         for (unsigned j = 0; j < 16; ++j) { const unsigned c = xb_ld(&bar[XB_XCNT(j)]); sum += c; cnt += (c > 0u) ? 1u : 0u; mine = (j == x) ? c : mine; }
;         if (sum == G) break;
;         __builtin_amdgcn_s_sleep(1);
;         if ((++sp & 255u) == 0u) { if (xb_ld(&bar[XB_TMO])) break; if (sp > XB_SPIN_CAP) { atomicAdd(&bar[XB_TMO], 1u); break; } }
;     }
;     nloc = mine > 0u ? mine : 1u; nx = cnt > 0u ? cnt : 1u;
; }
; __device__ __forceinline__ void xcd_barrier(const XcdBarrier& b) {
;     asm volatile("s_waitcnt vmcnt(0)" ::: "memory");
;     __syncthreads();
;     if (threadIdx.x == 0) {
;         unsigned* bar = b.bar;
;         __builtin_amdgcn_s_waitcnt(0);
;         unsigned nloc = b.st[0], nx = b.st[1];
;         if (nloc == 0u) { xcd_barrier_complete(bar, b.x, nloc, nx); b.st[0] = nloc; b.st[1] = nx; }
.Leinv_skip_7:
	s_mov_b64 s[0:1], exec
	v_readlane_b32 s2, v255, 2
	v_readlane_b32 s3, v255, 3
	v_readlane_b32 s48, v255, 5
	s_and_b64 s[2:3], s[0:1], s[2:3]
	v_readlane_b32 s49, v255, 6
	s_mov_b64 exec, s[2:3]
	s_cbranch_execz .LBB0_1305
	s_add_i32 s2, 0, 0x20000
	s_waitcnt vmcnt(15)
	v_mov_b32_e32 v0, s2
	s_waitcnt vmcnt(0) expcnt(0) lgkmcnt(0)
	ds_read_b32 v2, v0
	s_add_i32 s2, 0, 0x20004
	v_mov_b32_e32 v0, s2
	ds_read_b32 v0, v0
	s_waitcnt lgkmcnt(1)
	v_cmp_ne_u32_e32 vcc, 0, v2
	s_cbranch_vccnz .LBB0_1269
	s_add_u32 s4, s72, 0x580200
	s_addc_u32 s5, s73, 0
	s_add_u32 s6, s72, 0x580400
	s_addc_u32 s7, s73, 0
	s_add_u32 s8, s72, 0x580500
	s_addc_u32 s9, s73, 0
	s_add_u32 s10, s72, 0x580600
	s_addc_u32 s11, s73, 0
	s_add_u32 s14, s72, 0x580700
	s_addc_u32 s15, s73, 0
	s_add_u32 s16, s72, 0x580800
	s_addc_u32 s17, s73, 0
	s_add_u32 s18, s72, 0x580900
	s_addc_u32 s19, s73, 0
	s_add_u32 s20, s72, 0x580a00
	s_addc_u32 s21, s73, 0
	s_add_u32 s22, s72, 0x580b00
	s_addc_u32 s23, s73, 0
	s_add_u32 s24, s72, 0x580c00
	s_addc_u32 s25, s73, 0
	s_add_u32 s26, s72, 0x580d00
	s_addc_u32 s27, s73, 0
	s_add_u32 s28, s72, 0x580e00
	s_addc_u32 s29, s73, 0
	s_add_u32 s30, s72, 0x580f00
	s_addc_u32 s31, s73, 0
	s_add_u32 s34, s72, 0x581000
	s_addc_u32 s35, s73, 0
	s_add_u32 s36, s72, 0x581100
	s_addc_u32 s37, s73, 0
	s_add_u32 s38, s72, 0x581200
	v_readlane_b32 s2, v255, 0
	s_addc_u32 s39, s73, 0
	s_mul_i32 s2, s75, s2
	s_add_u32 s40, s72, 0x581300
	s_mul_i32 s2, s2, s74
	s_addc_u32 s41, s73, 0
	s_mov_b32 s3, 1
	v_mov_b32_e32 v16, 0
	s_branch .LBB0_1257
